# SSD dt prefix sum via DPP row_shr/row_bcast instead of six ds_bpermute hops; FFN fix-up rows processed 4 per trip with all loads issued up front
# speedup vs baseline: 1.0521x; 1.0062x over previous
.LBB0_320:
	s_or_b64 exec, exec, s[42:43]
	v_and_b32_e32 v24, 64, v197
	v_pk_mul_f32 v[20:21], v[128:129], v[18:19]
	v_add_f32_e32 v21, v20, v21
	v_mov_b32_e32 v23, v21
	s_nop 1
	v_add_f32_dpp v23, v23, v23 row_shr:1 row_mask:0xf bank_mask:0xf
	s_nop 1
	v_add_f32_dpp v23, v23, v23 row_shr:2 row_mask:0xf bank_mask:0xf
	s_nop 1
	v_add_f32_dpp v23, v23, v23 row_shr:4 row_mask:0xf bank_mask:0xf
	s_nop 1
	v_add_f32_dpp v23, v23, v23 row_shr:8 row_mask:0xf bank_mask:0xf
	s_nop 1
	v_add_f32_dpp v23, v23, v23 row_bcast:15 row_mask:0xa bank_mask:0xf
	s_nop 1
	v_add_f32_dpp v23, v23, v23 row_bcast:31 row_mask:0xc bank_mask:0xf
	s_nop 1
	v_sub_f32_e32 v21, v23, v21
	v_add_f32_e32 v22, v20, v21
	v_bfrev_b32_e32 v20, 0.5
	v_lshl_or_b32 v20, v197, 2, v20
	ds_bpermute_b32 v21, v20, v23
	ds_write_b64 v148, v[18:19]
	ds_write_b64 v149, v[22:23]
	s_waitcnt lgkmcnt(2)
	v_sub_f32_e32 v20, v21, v22
	v_sub_f32_e32 v21, v21, v23
	v_exp_f32_e32 v20, v20
	v_exp_f32_e32 v21, v21
	s_nop 0
	v_pk_mul_f32 v[20:21], v[18:19], v[20:21]
	ds_write_b64 v150, v[20:21]
	v_exp_f32_e32 v20, v22
	v_exp_f32_e32 v21, v23
	ds_write_b64 v151, v[20:21]
	v_or_b32_e32 v20, v24, v152
	v_lshlrev_b32_e32 v20, 2, v20
	ds_bpermute_b32 v20, v20, v23
	s_waitcnt lgkmcnt(0)
	v_sub_f32_e32 v21, v20, v22
	v_exp_f32_e32 v22, v21
	v_sub_f32_e32 v21, v20, v23
	v_exp_f32_e32 v23, v21
	s_nop 0
	v_pk_mul_f32 v[18:19], v[18:19], v[22:23]
	ds_write_b64 v153, v[18:19]
	s_and_b64 exec, exec, s[50:51]
	ds_write_b32 v154, v20

.LBB0_804:
	s_or_b64 exec, exec, s[0:1]
	s_mov_b64 s[2:3], s[94:95]
	v_mov_b32_e32 v0, v1
	s_waitcnt lgkmcnt(0)
	s_barrier
	s_mov_b32 s0, 0x580000
	v_mbcnt_lo_u32_b32 v0, -1, v0
	v_mbcnt_hi_u32_b32 v0, -1, v0
	v_add_u32_e32 v0, s93, v0
	s_nop 0
	v_add_u32_e32 v16, s76, v0
	v_cmp_gt_i32_e32 vcc, s0, v16
	s_and_saveexec_b64 s[0:1], vcc
	s_cbranch_execz .LBB0_819
	s_load_dwordx2 s[4:5], s[2:3], 0xc0
	s_load_dwordx4 s[8:11], s[2:3], 0x98
	v_lshlrev_b32_e32 v17, 1, v16
	s_waitcnt lgkmcnt(0)
	s_add_u32 s2, s4, 0x26000000
	s_addc_u32 s3, s5, 0
	s_add_u32 s4, s4, 0x8000000
	s_addc_u32 s5, s5, 0
	s_add_u32 s6, s8, s49
	s_addc_u32 s7, s9, 0
	s_add_u32 s8, s10, s48
	s_addc_u32 s9, s11, 0
	s_lshl_b32 s14, s74, 1
	s_mov_b64 s[10:11], 0
	s_mov_b32 s16, 0xffffa800
	s_mov_b32 s17, -1
	s_mov_b32 s98, 0xffff5000
	s_mov_b32 s99, -1
.Lfx_loop:
	s_mul_i32 s12, s74, 3
	s_mov_b32 s13, 0x580000
	v_add_u32_e32 v0, s12, v16
	v_cmp_gt_i32_e32 vcc, s13, v0
	s_nop 1
	s_andn2_b64 s[12:13], exec, vcc
	s_cmp_eq_u64 s[12:13], 0
	s_cbranch_scc0 .Lfx_tail
	s_mov_b32 s12, 0x2e8ba2e9
	v_mul_hi_i32 v0, v16, s12
	v_lshrrev_b32_e32 v2, 31, v0
	v_ashrrev_i32_e32 v0, 9, v0
	v_add_u32_e32 v0, v0, v2
	v_ashrrev_i32_e32 v18, 1, v0
	v_and_b32_e32 v19, 1, v0
	v_mul_i32_i24_e32 v3, 0xb00, v0
	v_sub_u32_e32 v2, v16, v3
	v_lshlrev_b32_e32 v3, 1, v3
	v_and_b32_e32 v4, 0x7f, v2
	v_sub_u32_e32 v3, v17, v3
	s_movk_i32 s12, 0xff00
	v_and_or_b32 v14, v3, s12, v4
	v_lshl_or_b32 v3, v18, 2, v19
	v_mul_hi_i32_i24_e32 v5, 0x5800, v3
	v_mul_i32_i24_e32 v4, 0x5800, v3
	v_lshl_add_u64 v[4:5], s[2:3], 0, v[4:5]
	v_ashrrev_i32_e32 v15, 31, v14
	v_lshl_add_u64 v[6:7], v[14:15], 2, v[4:5]
	v_lshl_add_u64 v[8:9], v[6:7], 0, s[16:17]
	v_lshl_add_u64 v[10:11], v[6:7], 0, s[98:99]
	global_load_dword v30, v[6:7], off
	global_load_dword v31, v[6:7], off offset:512
	global_load_dword v32, v[8:9], off
	global_load_dword v33, v[8:9], off offset:512
	global_load_dword v34, v[10:11], off
	global_load_dword v35, v[10:11], off offset:512
	v_and_b32_e32 v3, 0x7f, v0
	v_and_b32_e32 v4, 0x7e, v0
	v_cmp_ne_u32_e32 vcc, 0, v3
	s_nop 1
	v_cndmask_b32_e64 v46, 0, -1, vcc
	v_cmp_ne_u32_e32 vcc, 0, v4
	s_nop 1
	v_cndmask_b32_e64 v47, 0, -1, vcc
	v_lshl_or_b32 v6, v18, 6, v19
	v_mov_b64_e32 v[4:5], s[4:5]
	v_mad_i64_i32 v[4:5], s[12:13], v6, s82, v[4:5]
	v_ashrrev_i32_e32 v3, 31, v2
	v_lshl_add_u64 v[44:45], v[2:3], 1, v[4:5]
	v_lshlrev_b64 v[10:11], 2, v[2:3]
	v_lshl_add_u64 v[12:13], s[8:9], 0, v[10:11]
	v_lshl_add_u64 v[10:11], s[6:7], 0, v[10:11]
	v_add_co_u32_e32 v20, vcc, 0x5000, v10
	v_add_u32_e32 v0, 0xb00, v2
	s_nop 0
	v_addc_co_u32_e32 v21, vcc, 0, v11, vcc
	v_add_co_u32_e32 v22, vcc, 0xb000, v10
	v_lshlrev_b64 v[24:25], 2, v[0:1]
	s_nop 0
	v_addc_co_u32_e32 v23, vcc, 0, v11, vcc
	v_lshl_add_u64 v[26:27], s[8:9], 0, v[24:25]
	v_lshl_add_u64 v[24:25], s[6:7], 0, v[24:25]
	s_mov_b32 s12, 0x8000
	global_load_dword v40, v[20:21], off offset:2048
	global_load_dword v42, v[22:23], off
	global_load_dword v37, v[24:25], off
	v_add_co_u32_e32 v24, vcc, s12, v10
	global_load_dword v38, v[12:13], off
	s_nop 0
	v_addc_co_u32_e32 v25, vcc, 0, v11, vcc
	global_load_dword v36, v[10:11], off
	global_load_dword v39, v[26:27], off
	v_add_co_u32_e32 v10, vcc, 0xd000, v10
	global_load_dword v41, v[24:25], off offset:1024
	s_nop 0
	v_addc_co_u32_e32 v11, vcc, 0, v11, vcc
	global_load_dword v43, v[10:11], off offset:3072
	v_add_u32_e32 v16, s74, v16
	v_add_u32_e32 v17, s14, v17
	s_mov_b32 s12, 0x2e8ba2e9
	v_mul_hi_i32 v0, v16, s12
	v_lshrrev_b32_e32 v2, 31, v0
	v_ashrrev_i32_e32 v0, 9, v0
	v_add_u32_e32 v0, v0, v2
	v_ashrrev_i32_e32 v18, 1, v0
	v_and_b32_e32 v19, 1, v0
	v_mul_i32_i24_e32 v3, 0xb00, v0
	v_sub_u32_e32 v2, v16, v3
	v_lshlrev_b32_e32 v3, 1, v3
	v_and_b32_e32 v4, 0x7f, v2
	v_sub_u32_e32 v3, v17, v3
	s_movk_i32 s12, 0xff00
	v_and_or_b32 v14, v3, s12, v4
	v_lshl_or_b32 v3, v18, 2, v19
	v_mul_hi_i32_i24_e32 v5, 0x5800, v3
	v_mul_i32_i24_e32 v4, 0x5800, v3
	v_lshl_add_u64 v[4:5], s[2:3], 0, v[4:5]
	v_ashrrev_i32_e32 v15, 31, v14
	v_lshl_add_u64 v[6:7], v[14:15], 2, v[4:5]
	v_lshl_add_u64 v[8:9], v[6:7], 0, s[16:17]
	v_lshl_add_u64 v[10:11], v[6:7], 0, s[98:99]
	global_load_dword v50, v[6:7], off
	global_load_dword v51, v[6:7], off offset:512
	global_load_dword v52, v[8:9], off
	global_load_dword v53, v[8:9], off offset:512
	global_load_dword v54, v[10:11], off
	global_load_dword v55, v[10:11], off offset:512
	v_and_b32_e32 v3, 0x7f, v0
	v_and_b32_e32 v4, 0x7e, v0
	v_cmp_ne_u32_e32 vcc, 0, v3
	s_nop 1
	v_cndmask_b32_e64 v66, 0, -1, vcc
	v_cmp_ne_u32_e32 vcc, 0, v4
	s_nop 1
	v_cndmask_b32_e64 v67, 0, -1, vcc
	v_lshl_or_b32 v6, v18, 6, v19
	v_mov_b64_e32 v[4:5], s[4:5]
	v_mad_i64_i32 v[4:5], s[12:13], v6, s82, v[4:5]
	v_ashrrev_i32_e32 v3, 31, v2
	v_lshl_add_u64 v[64:65], v[2:3], 1, v[4:5]
	v_lshlrev_b64 v[10:11], 2, v[2:3]
	v_lshl_add_u64 v[12:13], s[8:9], 0, v[10:11]
	v_lshl_add_u64 v[10:11], s[6:7], 0, v[10:11]
	v_add_co_u32_e32 v20, vcc, 0x5000, v10
	v_add_u32_e32 v0, 0xb00, v2
	s_nop 0
	v_addc_co_u32_e32 v21, vcc, 0, v11, vcc
	v_add_co_u32_e32 v22, vcc, 0xb000, v10
	v_lshlrev_b64 v[24:25], 2, v[0:1]
	s_nop 0
	v_addc_co_u32_e32 v23, vcc, 0, v11, vcc
	v_lshl_add_u64 v[26:27], s[8:9], 0, v[24:25]
	v_lshl_add_u64 v[24:25], s[6:7], 0, v[24:25]
	s_mov_b32 s12, 0x8000
	global_load_dword v60, v[20:21], off offset:2048
	global_load_dword v62, v[22:23], off
	global_load_dword v57, v[24:25], off
	v_add_co_u32_e32 v24, vcc, s12, v10
	global_load_dword v58, v[12:13], off
	s_nop 0
	v_addc_co_u32_e32 v25, vcc, 0, v11, vcc
	global_load_dword v56, v[10:11], off
	global_load_dword v59, v[26:27], off
	v_add_co_u32_e32 v10, vcc, 0xd000, v10
	global_load_dword v61, v[24:25], off offset:1024
	s_nop 0
	v_addc_co_u32_e32 v11, vcc, 0, v11, vcc
	global_load_dword v63, v[10:11], off offset:3072
	v_add_u32_e32 v16, s74, v16
	v_add_u32_e32 v17, s14, v17
	s_mov_b32 s12, 0x2e8ba2e9
	v_mul_hi_i32 v0, v16, s12
	v_lshrrev_b32_e32 v2, 31, v0
	v_ashrrev_i32_e32 v0, 9, v0
	v_add_u32_e32 v0, v0, v2
	v_ashrrev_i32_e32 v18, 1, v0
	v_and_b32_e32 v19, 1, v0
	v_mul_i32_i24_e32 v3, 0xb00, v0
	v_sub_u32_e32 v2, v16, v3
	v_lshlrev_b32_e32 v3, 1, v3
	v_and_b32_e32 v4, 0x7f, v2
	v_sub_u32_e32 v3, v17, v3
	s_movk_i32 s12, 0xff00
	v_and_or_b32 v14, v3, s12, v4
	v_lshl_or_b32 v3, v18, 2, v19
	v_mul_hi_i32_i24_e32 v5, 0x5800, v3
	v_mul_i32_i24_e32 v4, 0x5800, v3
	v_lshl_add_u64 v[4:5], s[2:3], 0, v[4:5]
	v_ashrrev_i32_e32 v15, 31, v14
	v_lshl_add_u64 v[6:7], v[14:15], 2, v[4:5]
	v_lshl_add_u64 v[8:9], v[6:7], 0, s[16:17]
	v_lshl_add_u64 v[10:11], v[6:7], 0, s[98:99]
	global_load_dword v70, v[6:7], off
	global_load_dword v71, v[6:7], off offset:512
	global_load_dword v72, v[8:9], off
	global_load_dword v73, v[8:9], off offset:512
	global_load_dword v74, v[10:11], off
	global_load_dword v75, v[10:11], off offset:512
	v_and_b32_e32 v3, 0x7f, v0
	v_and_b32_e32 v4, 0x7e, v0
	v_cmp_ne_u32_e32 vcc, 0, v3
	s_nop 1
	v_cndmask_b32_e64 v86, 0, -1, vcc
	v_cmp_ne_u32_e32 vcc, 0, v4
	s_nop 1
	v_cndmask_b32_e64 v87, 0, -1, vcc
	v_lshl_or_b32 v6, v18, 6, v19
	v_mov_b64_e32 v[4:5], s[4:5]
	v_mad_i64_i32 v[4:5], s[12:13], v6, s82, v[4:5]
	v_ashrrev_i32_e32 v3, 31, v2
	v_lshl_add_u64 v[84:85], v[2:3], 1, v[4:5]
	v_lshlrev_b64 v[10:11], 2, v[2:3]
	v_lshl_add_u64 v[12:13], s[8:9], 0, v[10:11]
	v_lshl_add_u64 v[10:11], s[6:7], 0, v[10:11]
	v_add_co_u32_e32 v20, vcc, 0x5000, v10
	v_add_u32_e32 v0, 0xb00, v2
	s_nop 0
	v_addc_co_u32_e32 v21, vcc, 0, v11, vcc
	v_add_co_u32_e32 v22, vcc, 0xb000, v10
	v_lshlrev_b64 v[24:25], 2, v[0:1]
	s_nop 0
	v_addc_co_u32_e32 v23, vcc, 0, v11, vcc
	v_lshl_add_u64 v[26:27], s[8:9], 0, v[24:25]
	v_lshl_add_u64 v[24:25], s[6:7], 0, v[24:25]
	s_mov_b32 s12, 0x8000
	global_load_dword v80, v[20:21], off offset:2048
	global_load_dword v82, v[22:23], off
	global_load_dword v77, v[24:25], off
	v_add_co_u32_e32 v24, vcc, s12, v10
	global_load_dword v78, v[12:13], off
	s_nop 0
	v_addc_co_u32_e32 v25, vcc, 0, v11, vcc
	global_load_dword v76, v[10:11], off
	global_load_dword v79, v[26:27], off
	v_add_co_u32_e32 v10, vcc, 0xd000, v10
	global_load_dword v81, v[24:25], off offset:1024
	s_nop 0
	v_addc_co_u32_e32 v11, vcc, 0, v11, vcc
	global_load_dword v83, v[10:11], off offset:3072
	v_add_u32_e32 v16, s74, v16
	v_add_u32_e32 v17, s14, v17
	s_mov_b32 s12, 0x2e8ba2e9
	v_mul_hi_i32 v0, v16, s12
	v_lshrrev_b32_e32 v2, 31, v0
	v_ashrrev_i32_e32 v0, 9, v0
	v_add_u32_e32 v0, v0, v2
	v_ashrrev_i32_e32 v18, 1, v0
	v_and_b32_e32 v19, 1, v0
	v_mul_i32_i24_e32 v3, 0xb00, v0
	v_sub_u32_e32 v2, v16, v3
	v_lshlrev_b32_e32 v3, 1, v3
	v_and_b32_e32 v4, 0x7f, v2
	v_sub_u32_e32 v3, v17, v3
	s_movk_i32 s12, 0xff00
	v_and_or_b32 v14, v3, s12, v4
	v_lshl_or_b32 v3, v18, 2, v19
	v_mul_hi_i32_i24_e32 v5, 0x5800, v3
	v_mul_i32_i24_e32 v4, 0x5800, v3
	v_lshl_add_u64 v[4:5], s[2:3], 0, v[4:5]
	v_ashrrev_i32_e32 v15, 31, v14
	v_lshl_add_u64 v[6:7], v[14:15], 2, v[4:5]
	v_lshl_add_u64 v[8:9], v[6:7], 0, s[16:17]
	v_lshl_add_u64 v[10:11], v[6:7], 0, s[98:99]
	global_load_dword v90, v[6:7], off
	global_load_dword v91, v[6:7], off offset:512
	global_load_dword v92, v[8:9], off
	global_load_dword v93, v[8:9], off offset:512
	global_load_dword v94, v[10:11], off
	global_load_dword v95, v[10:11], off offset:512
	v_and_b32_e32 v3, 0x7f, v0
	v_and_b32_e32 v4, 0x7e, v0
	v_cmp_ne_u32_e32 vcc, 0, v3
	s_nop 1
	v_cndmask_b32_e64 v106, 0, -1, vcc
	v_cmp_ne_u32_e32 vcc, 0, v4
	s_nop 1
	v_cndmask_b32_e64 v107, 0, -1, vcc
	v_lshl_or_b32 v6, v18, 6, v19
	v_mov_b64_e32 v[4:5], s[4:5]
	v_mad_i64_i32 v[4:5], s[12:13], v6, s82, v[4:5]
	v_ashrrev_i32_e32 v3, 31, v2
	v_lshl_add_u64 v[104:105], v[2:3], 1, v[4:5]
	v_lshlrev_b64 v[10:11], 2, v[2:3]
	v_lshl_add_u64 v[12:13], s[8:9], 0, v[10:11]
	v_lshl_add_u64 v[10:11], s[6:7], 0, v[10:11]
	v_add_co_u32_e32 v20, vcc, 0x5000, v10
	v_add_u32_e32 v0, 0xb00, v2
	s_nop 0
	v_addc_co_u32_e32 v21, vcc, 0, v11, vcc
	v_add_co_u32_e32 v22, vcc, 0xb000, v10
	v_lshlrev_b64 v[24:25], 2, v[0:1]
	s_nop 0
	v_addc_co_u32_e32 v23, vcc, 0, v11, vcc
	v_lshl_add_u64 v[26:27], s[8:9], 0, v[24:25]
	v_lshl_add_u64 v[24:25], s[6:7], 0, v[24:25]
	s_mov_b32 s12, 0x8000
	global_load_dword v100, v[20:21], off offset:2048
	global_load_dword v102, v[22:23], off
	global_load_dword v97, v[24:25], off
	v_add_co_u32_e32 v24, vcc, s12, v10
	global_load_dword v98, v[12:13], off
	s_nop 0
	v_addc_co_u32_e32 v25, vcc, 0, v11, vcc
	global_load_dword v96, v[10:11], off
	global_load_dword v99, v[26:27], off
	v_add_co_u32_e32 v10, vcc, 0xd000, v10
	global_load_dword v101, v[24:25], off offset:1024
	s_nop 0
	v_addc_co_u32_e32 v11, vcc, 0, v11, vcc
	global_load_dword v103, v[10:11], off offset:3072
	v_add_u32_e32 v16, s74, v16
	v_add_u32_e32 v17, s14, v17
	s_waitcnt vmcnt(42)
	v_and_b32_e32 v32, v32, v46
	v_and_b32_e32 v33, v33, v46
	v_and_b32_e32 v34, v34, v47
	v_and_b32_e32 v35, v35, v47
	v_pk_fma_f32 v[8:9], v[34:35], v[36:37], v[38:39]
	v_pk_fma_f32 v[6:7], v[32:33], v[40:41], v[8:9]
	v_pk_fma_f32 v[4:5], v[30:31], v[42:43], v[6:7]
	s_nop 0
	v_mul_f32_e32 v0, 0xbfb8aa3b, v4
	v_exp_f32_e32 v0, v0
	s_nop 0
	v_add_f32_e32 v0, 1.0, v0
	v_div_scale_f32 v6, s[12:13], v0, v0, v4
	v_rcp_f32_e32 v7, v6
	s_movk_i32 s12, 0x7fff
	v_fma_f32 v8, -v6, v7, 1.0
	v_fmac_f32_e32 v7, v8, v7
	v_div_scale_f32 v8, vcc, v4, v0, v4
	v_mul_f32_e32 v9, v8, v7
	v_fma_f32 v10, -v6, v9, v8
	v_fmac_f32_e32 v9, v10, v7
	v_fma_f32 v6, -v6, v9, v8
	v_div_fmas_f32 v6, v6, v7, v9
	v_div_fixup_f32 v0, v6, v0, v4
	v_mul_f32_e32 v0, v0, v5
	v_bfe_u32 v4, v0, 16, 1
	v_add3_u32 v0, v0, v4, s12
	global_store_short_d16_hi v[44:45], v0, off
	s_waitcnt vmcnt(29)
	v_and_b32_e32 v52, v52, v66
	v_and_b32_e32 v53, v53, v66
	v_and_b32_e32 v54, v54, v67
	v_and_b32_e32 v55, v55, v67
	v_pk_fma_f32 v[8:9], v[54:55], v[56:57], v[58:59]
	v_pk_fma_f32 v[6:7], v[52:53], v[60:61], v[8:9]
	v_pk_fma_f32 v[4:5], v[50:51], v[62:63], v[6:7]
	s_nop 0
	v_mul_f32_e32 v0, 0xbfb8aa3b, v4
	v_exp_f32_e32 v0, v0
	s_nop 0
	v_add_f32_e32 v0, 1.0, v0
	v_div_scale_f32 v6, s[12:13], v0, v0, v4
	v_rcp_f32_e32 v7, v6
	s_movk_i32 s12, 0x7fff
	v_fma_f32 v8, -v6, v7, 1.0
	v_fmac_f32_e32 v7, v8, v7
	v_div_scale_f32 v8, vcc, v4, v0, v4
	v_mul_f32_e32 v9, v8, v7
	v_fma_f32 v10, -v6, v9, v8
	v_fmac_f32_e32 v9, v10, v7
	v_fma_f32 v6, -v6, v9, v8
	v_div_fmas_f32 v6, v6, v7, v9
	v_div_fixup_f32 v0, v6, v0, v4
	v_mul_f32_e32 v0, v0, v5
	v_bfe_u32 v4, v0, 16, 1
	v_add3_u32 v0, v0, v4, s12
	global_store_short_d16_hi v[64:65], v0, off
	s_waitcnt vmcnt(16)
	v_and_b32_e32 v72, v72, v86
	v_and_b32_e32 v73, v73, v86
	v_and_b32_e32 v74, v74, v87
	v_and_b32_e32 v75, v75, v87
	v_pk_fma_f32 v[8:9], v[74:75], v[76:77], v[78:79]
	v_pk_fma_f32 v[6:7], v[72:73], v[80:81], v[8:9]
	v_pk_fma_f32 v[4:5], v[70:71], v[82:83], v[6:7]
	s_nop 0
	v_mul_f32_e32 v0, 0xbfb8aa3b, v4
	v_exp_f32_e32 v0, v0
	s_nop 0
	v_add_f32_e32 v0, 1.0, v0
	v_div_scale_f32 v6, s[12:13], v0, v0, v4
	v_rcp_f32_e32 v7, v6
	s_movk_i32 s12, 0x7fff
	v_fma_f32 v8, -v6, v7, 1.0
	v_fmac_f32_e32 v7, v8, v7
	v_div_scale_f32 v8, vcc, v4, v0, v4
	v_mul_f32_e32 v9, v8, v7
	v_fma_f32 v10, -v6, v9, v8
	v_fmac_f32_e32 v9, v10, v7
	v_fma_f32 v6, -v6, v9, v8
	v_div_fmas_f32 v6, v6, v7, v9
	v_div_fixup_f32 v0, v6, v0, v4
	v_mul_f32_e32 v0, v0, v5
	v_bfe_u32 v4, v0, 16, 1
	v_add3_u32 v0, v0, v4, s12
	global_store_short_d16_hi v[84:85], v0, off
	s_waitcnt vmcnt(3)
	v_and_b32_e32 v92, v92, v106
	v_and_b32_e32 v93, v93, v106
	v_and_b32_e32 v94, v94, v107
	v_and_b32_e32 v95, v95, v107
	v_pk_fma_f32 v[8:9], v[94:95], v[96:97], v[98:99]
	v_pk_fma_f32 v[6:7], v[92:93], v[100:101], v[8:9]
	v_pk_fma_f32 v[4:5], v[90:91], v[102:103], v[6:7]
	s_nop 0
	v_mul_f32_e32 v0, 0xbfb8aa3b, v4
	v_exp_f32_e32 v0, v0
	s_nop 0
	v_add_f32_e32 v0, 1.0, v0
	v_div_scale_f32 v6, s[12:13], v0, v0, v4
	v_rcp_f32_e32 v7, v6
	s_movk_i32 s12, 0x7fff
	v_fma_f32 v8, -v6, v7, 1.0
	v_fmac_f32_e32 v7, v8, v7
	v_div_scale_f32 v8, vcc, v4, v0, v4
	v_mul_f32_e32 v9, v8, v7
	v_fma_f32 v10, -v6, v9, v8
	v_fmac_f32_e32 v9, v10, v7
	v_fma_f32 v6, -v6, v9, v8
	v_div_fmas_f32 v6, v6, v7, v9
	v_div_fixup_f32 v0, v6, v0, v4
	v_mul_f32_e32 v0, v0, v5
	v_bfe_u32 v4, v0, 16, 1
	v_add3_u32 v0, v0, v4, s12
	global_store_short_d16_hi v[104:105], v0, off
	s_branch .Lfx_loop
.Lfx_tail:
	s_mov_b32 s12, 0x57ffff
	v_cmp_lt_i32_e32 vcc, s12, v16
	s_nop 1
	s_or_b64 s[10:11], vcc, s[10:11]
	s_andn2_b64 exec, exec, s[10:11]
	s_cbranch_execz .LBB0_819
	s_branch .LBB0_807
